# gate-tile stores sc0 sc1 nt; + no entry grid.sync
# speedup vs baseline: 1.0040x; 1.0040x over previous
; __device__ __forceinline__ float sigm(float v) { return __builtin_amdgcn_rcpf(1.0f + __builtin_amdgcn_exp2f(-LOG2E * v)); }
; __device__ __forceinline__ unsigned cvt_pk_bf16(float lo, float hi) { f32x2_t v = {lo, hi}; bf16x2_t b = __builtin_convertvector(v, bf16x2_t); return __builtin_bit_cast(unsigned, b); }
; template <int MODE> __device__ __forceinline__ float actf(float v) {
;     if (MODE == 1) return v * sigm(v);
;     if (MODE == 2) return fminf(1.0f + __builtin_amdgcn_exp2f(-LOG2E * v), 1e30f);
;     template <int MODE> __device__ __forceinline__ void run(const f32x4 (&acc)[2][2][4][2], const Unit& u, int wr, int wc, int fr, int fq) const {
;     ...
;         for (int bj = 0; bj < 2; ++bj) {
; #pragma unroll
;             for (int ai = 0; ai < 2; ++ai)
; #pragma unroll
;                 for (int m = 0; m < 4; ++m) { const unsigned off = off0 + ((MODE == 2) ? (unsigned)(((ai * 4 + m) * 2 + bj) * 1024) : (unsigned)((ai * HALF + m * 16) * 512 + bj * HALF) * 2u);
;                     const f32x4 v0 = acc[ai][bj][m][0], v1 = acc[ai][bj][m][1];
;                     u32x4 w; w.x = cvt_pk_bf16(actf<MODE>(v0[0]), actf<MODE>(v0[1])); w.y = cvt_pk_bf16(actf<MODE>(v0[2]), actf<MODE>(v0[3]));
;                     w.z = cvt_pk_bf16(actf<MODE>(v1[0]), actf<MODE>(v1[1])); w.w = cvt_pk_bf16(actf<MODE>(v1[2]), actf<MODE>(v1[3]));
;                     *(u32x4*)(base + off) = w; }
.LBB0_403:
	v_mul_f32_e32 v12, 0xbfb8aa3b, v12
	v_mul_f32_e32 v13, 0xbfb8aa3b, v13
	v_exp_f32_e32 v12, v12
	v_exp_f32_e32 v13, v13
	v_mul_f32_e32 v14, 0xbfb8aa3b, v14
	v_mul_f32_e32 v15, 0xbfb8aa3b, v15
	v_mul_f32_e32 v8, 0xbfb8aa3b, v8
	v_mul_f32_e32 v9, 0xbfb8aa3b, v9
	v_exp_f32_e32 v14, v14
	v_exp_f32_e32 v15, v15
	v_exp_f32_e32 v8, v8
	v_exp_f32_e32 v9, v9
	v_mul_f32_e32 v10, 0xbfb8aa3b, v10
	v_mul_f32_e32 v11, 0xbfb8aa3b, v11
	v_add_f32_e32 v12, 1.0, v12
	v_add_f32_e32 v13, 1.0, v13
	v_exp_f32_e32 v10, v10
	v_exp_f32_e32 v11, v11
	v_mul_f32_e32 v76, 0xbfb8aa3b, v76
	v_mul_f32_e32 v77, 0xbfb8aa3b, v77
	v_min_f32_e32 v12, 0x7149f2ca, v12
	v_min_f32_e32 v13, 0x7149f2ca, v13
	v_exp_f32_e32 v76, v76
	v_exp_f32_e32 v77, v77
	v_cvt_pk_bf16_f32 v12, v12, v13
	v_add_f32_e32 v13, 1.0, v14
	v_add_f32_e32 v14, 1.0, v15
	v_add_f32_e32 v8, 1.0, v8
	v_add_f32_e32 v9, 1.0, v9
	v_mul_f32_e32 v78, 0xbfb8aa3b, v78
	v_mul_f32_e32 v79, 0xbfb8aa3b, v79
	v_mul_f32_e32 v72, 0xbfb8aa3b, v72
	v_mul_f32_e32 v73, 0xbfb8aa3b, v73
	v_min_f32_e32 v13, 0x7149f2ca, v13
	v_min_f32_e32 v14, 0x7149f2ca, v14
	v_min_f32_e32 v8, 0x7149f2ca, v8
	v_min_f32_e32 v9, 0x7149f2ca, v9
	v_mov_b32_e32 v142, v212
	s_lshl_b32 s60, s72, 7
	v_exp_f32_e32 v78, v78
	v_exp_f32_e32 v79, v79
	v_exp_f32_e32 v72, v72
	v_exp_f32_e32 v73, v73
	v_cvt_pk_bf16_f32 v13, v13, v14
	v_cvt_pk_bf16_f32 v14, v8, v9
	v_add_f32_e32 v8, 1.0, v10
	v_add_f32_e32 v9, 1.0, v11
	s_add_i32 s60, s60, s54
	v_readfirstlane_b32 s55, v142
	v_mul_f32_e32 v74, 0xbfb8aa3b, v74
	v_mul_f32_e32 v75, 0xbfb8aa3b, v75
	v_min_f32_e32 v8, 0x7149f2ca, v8
	v_min_f32_e32 v9, 0x7149f2ca, v9
	s_ashr_i32 s55, s55, 6
	s_lshl_b32 s54, s60, 3
	v_add_f32_e32 v76, 1.0, v76
	v_add_f32_e32 v77, 1.0, v77
	v_exp_f32_e32 v74, v74
	v_exp_f32_e32 v75, v75
	v_cvt_pk_bf16_f32 v15, v8, v9
	v_mul_f32_e32 v8, 0xbfb8aa3b, v68
	v_mul_f32_e32 v9, 0xbfb8aa3b, v69
	s_add_i32 s54, s54, s55
	v_min_f32_e32 v76, 0x7149f2ca, v76
	v_min_f32_e32 v77, 0x7149f2ca, v77
	v_exp_f32_e32 v8, v8
	v_exp_f32_e32 v9, v9
	s_addk_i32 s54, 0xd000
	v_cvt_pk_bf16_f32 v76, v76, v77
	v_add_f32_e32 v77, 1.0, v78
	v_add_f32_e32 v78, 1.0, v79
	v_add_f32_e32 v72, 1.0, v72
	v_add_f32_e32 v73, 1.0, v73
	v_mul_f32_e32 v10, 0xbfb8aa3b, v70
	v_mul_f32_e32 v11, 0xbfb8aa3b, v71
	s_ashr_i32 s55, s54, 31
	v_min_f32_e32 v77, 0x7149f2ca, v77
	v_min_f32_e32 v78, 0x7149f2ca, v78
	v_min_f32_e32 v72, 0x7149f2ca, v72
	v_min_f32_e32 v73, 0x7149f2ca, v73
	v_exp_f32_e32 v10, v10
	v_exp_f32_e32 v11, v11
	s_lshl_b64 s[54:55], s[54:55], 14
	v_lshlrev_b32_e32 v142, 4, v142
	v_cvt_pk_bf16_f32 v77, v77, v78
	v_cvt_pk_bf16_f32 v78, v72, v73
	v_add_f32_e32 v72, 1.0, v74
	v_add_f32_e32 v73, 1.0, v75
	s_add_u32 s54, s33, s54
	v_and_b32_e32 v142, 0x3f0, v142
	v_min_f32_e32 v72, 0x7149f2ca, v72
	v_min_f32_e32 v73, 0x7149f2ca, v73
	v_add_f32_e32 v8, 1.0, v8
	v_add_f32_e32 v9, 1.0, v9
	s_addc_u32 s55, s37, s55
	v_cvt_pk_bf16_f32 v79, v72, v73
	v_add_u32_e32 v72, 0x3800, v142
	v_min_f32_e32 v8, 0x7149f2ca, v8
	v_min_f32_e32 v9, 0x7149f2ca, v9
	v_mul_f32_e32 v126, 0xbfb8aa3b, v126
	v_mul_f32_e32 v127, 0xbfb8aa3b, v127
	v_mul_f32_e32 v118, 0xbfb8aa3b, v118
	v_mul_f32_e32 v119, 0xbfb8aa3b, v119
	v_mul_f32_e32 v110, 0xbfb8aa3b, v110
	v_mul_f32_e32 v111, 0xbfb8aa3b, v111
	v_mul_f32_e32 v102, 0xbfb8aa3b, v102
	v_mul_f32_e32 v103, 0xbfb8aa3b, v103
	v_mul_f32_e32 v92, 0xbfb8aa3b, v92
	v_mul_f32_e32 v93, 0xbfb8aa3b, v93
	v_mul_f32_e32 v84, 0xbfb8aa3b, v84
	v_mul_f32_e32 v85, 0xbfb8aa3b, v85
	global_store_dwordx4 v72, v[12:15], s[54:55] sc0 sc1 nt
	v_cvt_pk_bf16_f32 v8, v8, v9
	v_add_f32_e32 v9, 1.0, v10
	v_add_f32_e32 v10, 1.0, v11
	v_mul_f32_e32 v11, 0xbfb8aa3b, v64
	v_mul_f32_e32 v13, 0xbfb8aa3b, v65
	v_exp_f32_e32 v126, v126
	v_exp_f32_e32 v127, v127
	v_exp_f32_e32 v118, v118
	v_exp_f32_e32 v119, v119
	v_exp_f32_e32 v110, v110
	v_exp_f32_e32 v111, v111
	v_exp_f32_e32 v102, v102
	v_exp_f32_e32 v103, v103
	v_exp_f32_e32 v92, v92
	v_exp_f32_e32 v93, v93
	v_exp_f32_e32 v84, v84
	v_exp_f32_e32 v85, v85
	v_exp_f32_e32 v11, v11
	v_exp_f32_e32 v13, v13
	v_mul_f32_e32 v128, 0xbfb8aa3b, v128
	v_mul_f32_e32 v129, 0xbfb8aa3b, v129
	v_mul_f32_e32 v122, 0xbfb8aa3b, v122
	v_mul_f32_e32 v123, 0xbfb8aa3b, v123
	v_mul_f32_e32 v120, 0xbfb8aa3b, v120
	v_mul_f32_e32 v121, 0xbfb8aa3b, v121
	v_mul_f32_e32 v114, 0xbfb8aa3b, v114
	v_mul_f32_e32 v115, 0xbfb8aa3b, v115
	v_mul_f32_e32 v112, 0xbfb8aa3b, v112
	v_mul_f32_e32 v113, 0xbfb8aa3b, v113
	v_mul_f32_e32 v106, 0xbfb8aa3b, v106
	v_mul_f32_e32 v107, 0xbfb8aa3b, v107
	v_mul_f32_e32 v104, 0xbfb8aa3b, v104
	v_mul_f32_e32 v105, 0xbfb8aa3b, v105
	v_mul_f32_e32 v98, 0xbfb8aa3b, v98
	v_mul_f32_e32 v99, 0xbfb8aa3b, v99
	v_mul_f32_e32 v94, 0xbfb8aa3b, v94
	v_mul_f32_e32 v95, 0xbfb8aa3b, v95
	v_mul_f32_e32 v88, 0xbfb8aa3b, v88
	v_mul_f32_e32 v89, 0xbfb8aa3b, v89
	v_mul_f32_e32 v86, 0xbfb8aa3b, v86
	v_mul_f32_e32 v87, 0xbfb8aa3b, v87
	v_mul_f32_e32 v80, 0xbfb8aa3b, v80
	v_mul_f32_e32 v81, 0xbfb8aa3b, v81
	v_exp_f32_e32 v128, v128
	v_exp_f32_e32 v129, v129
	v_exp_f32_e32 v122, v122
	v_exp_f32_e32 v123, v123
	v_exp_f32_e32 v120, v120
	v_exp_f32_e32 v121, v121
	v_exp_f32_e32 v114, v114
	v_exp_f32_e32 v115, v115
	v_exp_f32_e32 v112, v112
	v_exp_f32_e32 v113, v113
	v_exp_f32_e32 v106, v106
	v_exp_f32_e32 v107, v107
	v_exp_f32_e32 v104, v104
	v_exp_f32_e32 v105, v105
	v_exp_f32_e32 v98, v98
	v_exp_f32_e32 v99, v99
	v_exp_f32_e32 v94, v94
	v_exp_f32_e32 v95, v95
	v_exp_f32_e32 v88, v88
	v_exp_f32_e32 v89, v89
	v_exp_f32_e32 v86, v86
	v_exp_f32_e32 v87, v87
	v_exp_f32_e32 v80, v80
	v_exp_f32_e32 v81, v81
	v_mul_f32_e32 v124, 0xbfb8aa3b, v124
	v_mul_f32_e32 v125, 0xbfb8aa3b, v125
	v_mul_f32_e32 v116, 0xbfb8aa3b, v116
; __device__ __forceinline__ float sigm(float v) { return __builtin_amdgcn_rcpf(1.0f + __builtin_amdgcn_exp2f(-LOG2E * v)); }
; __device__ __forceinline__ unsigned cvt_pk_bf16(float lo, float hi) { f32x2_t v = {lo, hi}; bf16x2_t b = __builtin_convertvector(v, bf16x2_t); return __builtin_bit_cast(unsigned, b); }
; template <int MODE> __device__ __forceinline__ float actf(float v) {
;     if (MODE == 1) return v * sigm(v);
;     if (MODE == 2) return fminf(1.0f + __builtin_amdgcn_exp2f(-LOG2E * v), 1e30f);
;     template <int MODE> __device__ __forceinline__ void run(const f32x4 (&acc)[2][2][4][2], const Unit& u, int wr, int wc, int fr, int fq) const {
;     ...
;         for (int bj = 0; bj < 2; ++bj) {
; #pragma unroll
;             for (int ai = 0; ai < 2; ++ai)
; #pragma unroll
;                 for (int m = 0; m < 4; ++m) { const unsigned off = off0 + ((MODE == 2) ? (unsigned)(((ai * 4 + m) * 2 + bj) * 1024) : (unsigned)((ai * HALF + m * 16) * 512 + bj * HALF) * 2u);
;                     const f32x4 v0 = acc[ai][bj][m][0], v1 = acc[ai][bj][m][1];
;                     u32x4 w; w.x = cvt_pk_bf16(actf<MODE>(v0[0]), actf<MODE>(v0[1])); w.y = cvt_pk_bf16(actf<MODE>(v0[2]), actf<MODE>(v0[3]));
;                     w.z = cvt_pk_bf16(actf<MODE>(v1[0]), actf<MODE>(v1[1])); w.w = cvt_pk_bf16(actf<MODE>(v1[2]), actf<MODE>(v1[3]));
;                     *(u32x4*)(base + off) = w; }
	v_mul_f32_e32 v117, 0xbfb8aa3b, v117
	v_mul_f32_e32 v108, 0xbfb8aa3b, v108
	v_mul_f32_e32 v109, 0xbfb8aa3b, v109
	v_mul_f32_e32 v100, 0xbfb8aa3b, v100
	v_mul_f32_e32 v101, 0xbfb8aa3b, v101
	v_mul_f32_e32 v90, 0xbfb8aa3b, v90
	v_mul_f32_e32 v91, 0xbfb8aa3b, v91
	v_mul_f32_e32 v82, 0xbfb8aa3b, v82
	v_mul_f32_e32 v83, 0xbfb8aa3b, v83
	v_min_f32_e32 v9, 0x7149f2ca, v9
	v_min_f32_e32 v10, 0x7149f2ca, v10
	v_add_f32_e32 v126, 1.0, v126
	v_add_f32_e32 v127, 1.0, v127
	v_exp_f32_e32 v124, v124
	v_exp_f32_e32 v125, v125
	v_add_f32_e32 v118, 1.0, v118
	v_add_f32_e32 v119, 1.0, v119
	v_exp_f32_e32 v116, v116
	v_exp_f32_e32 v117, v117
	v_add_f32_e32 v110, 1.0, v110
	v_add_f32_e32 v111, 1.0, v111
	v_exp_f32_e32 v108, v108
	v_exp_f32_e32 v109, v109
	v_add_f32_e32 v102, 1.0, v102
	v_add_f32_e32 v103, 1.0, v103
	v_exp_f32_e32 v100, v100
	v_exp_f32_e32 v101, v101
	v_add_f32_e32 v92, 1.0, v92
	v_add_f32_e32 v93, 1.0, v93
	v_exp_f32_e32 v90, v90
	v_exp_f32_e32 v91, v91
	v_add_f32_e32 v84, 1.0, v84
	v_add_f32_e32 v85, 1.0, v85
	v_exp_f32_e32 v82, v82
	v_exp_f32_e32 v83, v83
	v_cvt_pk_bf16_f32 v9, v9, v10
	v_add_f32_e32 v10, 1.0, v11
	v_add_f32_e32 v11, 1.0, v13
	v_mul_f32_e32 v13, 0xbfb8aa3b, v66
	v_mul_f32_e32 v14, 0xbfb8aa3b, v67
	v_min_f32_e32 v126, 0x7149f2ca, v126
	v_min_f32_e32 v127, 0x7149f2ca, v127
	v_min_f32_e32 v118, 0x7149f2ca, v118
	v_min_f32_e32 v119, 0x7149f2ca, v119
	v_min_f32_e32 v110, 0x7149f2ca, v110
	v_min_f32_e32 v111, 0x7149f2ca, v111
	v_min_f32_e32 v102, 0x7149f2ca, v102
	v_min_f32_e32 v103, 0x7149f2ca, v103
	v_min_f32_e32 v92, 0x7149f2ca, v92
	v_min_f32_e32 v93, 0x7149f2ca, v93
	v_min_f32_e32 v84, 0x7149f2ca, v84
	v_min_f32_e32 v85, 0x7149f2ca, v85
	v_exp_f32_e32 v13, v13
	v_exp_f32_e32 v14, v14
	v_cvt_pk_bf16_f32 v126, v126, v127
	v_add_f32_e32 v127, 1.0, v128
	v_add_f32_e32 v128, 1.0, v129
	v_add_f32_e32 v122, 1.0, v122
	v_add_f32_e32 v123, 1.0, v123
	v_cvt_pk_bf16_f32 v118, v118, v119
	v_add_f32_e32 v119, 1.0, v120
	v_add_f32_e32 v120, 1.0, v121
	v_add_f32_e32 v114, 1.0, v114
	v_add_f32_e32 v115, 1.0, v115
	v_cvt_pk_bf16_f32 v110, v110, v111
	v_add_f32_e32 v111, 1.0, v112
	v_add_f32_e32 v112, 1.0, v113
	v_add_f32_e32 v106, 1.0, v106
	v_add_f32_e32 v107, 1.0, v107
	v_cvt_pk_bf16_f32 v102, v102, v103
	v_add_f32_e32 v103, 1.0, v104
	v_add_f32_e32 v104, 1.0, v105
	v_add_f32_e32 v98, 1.0, v98
	v_add_f32_e32 v99, 1.0, v99
	v_cvt_pk_bf16_f32 v92, v92, v93
	v_add_f32_e32 v93, 1.0, v94
	v_add_f32_e32 v94, 1.0, v95
	v_add_f32_e32 v88, 1.0, v88
	v_add_f32_e32 v89, 1.0, v89
	v_cvt_pk_bf16_f32 v84, v84, v85
	v_add_f32_e32 v85, 1.0, v86
	v_add_f32_e32 v86, 1.0, v87
	v_add_f32_e32 v80, 1.0, v80
	v_add_f32_e32 v81, 1.0, v81
	v_min_f32_e32 v127, 0x7149f2ca, v127
	v_min_f32_e32 v128, 0x7149f2ca, v128
	v_min_f32_e32 v122, 0x7149f2ca, v122
	v_min_f32_e32 v123, 0x7149f2ca, v123
	v_min_f32_e32 v119, 0x7149f2ca, v119
	v_min_f32_e32 v120, 0x7149f2ca, v120
	v_min_f32_e32 v114, 0x7149f2ca, v114
	v_min_f32_e32 v115, 0x7149f2ca, v115
	v_min_f32_e32 v111, 0x7149f2ca, v111
	v_min_f32_e32 v112, 0x7149f2ca, v112
	v_min_f32_e32 v106, 0x7149f2ca, v106
	v_min_f32_e32 v107, 0x7149f2ca, v107
	v_min_f32_e32 v103, 0x7149f2ca, v103
	v_min_f32_e32 v104, 0x7149f2ca, v104
	v_min_f32_e32 v98, 0x7149f2ca, v98
	v_min_f32_e32 v99, 0x7149f2ca, v99
	v_min_f32_e32 v93, 0x7149f2ca, v93
	v_min_f32_e32 v94, 0x7149f2ca, v94
	v_min_f32_e32 v88, 0x7149f2ca, v88
	v_min_f32_e32 v89, 0x7149f2ca, v89
	v_min_f32_e32 v85, 0x7149f2ca, v85
	v_min_f32_e32 v86, 0x7149f2ca, v86
	v_min_f32_e32 v80, 0x7149f2ca, v80
	v_min_f32_e32 v81, 0x7149f2ca, v81
	v_cvt_pk_bf16_f32 v127, v127, v128
	v_cvt_pk_bf16_f32 v128, v122, v123
	v_add_f32_e32 v122, 1.0, v124
	v_add_f32_e32 v123, 1.0, v125
	v_cvt_pk_bf16_f32 v119, v119, v120
	v_cvt_pk_bf16_f32 v120, v114, v115
	v_add_f32_e32 v114, 1.0, v116
	v_add_f32_e32 v115, 1.0, v117
	v_cvt_pk_bf16_f32 v111, v111, v112
	v_cvt_pk_bf16_f32 v112, v106, v107
	v_add_f32_e32 v106, 1.0, v108
	v_add_f32_e32 v107, 1.0, v109
	v_cvt_pk_bf16_f32 v103, v103, v104
	v_cvt_pk_bf16_f32 v104, v98, v99
	v_add_f32_e32 v98, 1.0, v100
	v_add_f32_e32 v99, 1.0, v101
	v_cvt_pk_bf16_f32 v93, v93, v94
	v_cvt_pk_bf16_f32 v94, v88, v89
	v_add_f32_e32 v88, 1.0, v90
	v_add_f32_e32 v89, 1.0, v91
	v_cvt_pk_bf16_f32 v85, v85, v86
	v_cvt_pk_bf16_f32 v86, v80, v81
	v_add_f32_e32 v80, 1.0, v82
	v_add_f32_e32 v81, 1.0, v83
	v_min_f32_e32 v10, 0x7149f2ca, v10
	v_min_f32_e32 v11, 0x7149f2ca, v11
	v_min_f32_e32 v122, 0x7149f2ca, v122
	v_min_f32_e32 v123, 0x7149f2ca, v123
	v_min_f32_e32 v114, 0x7149f2ca, v114
	v_min_f32_e32 v115, 0x7149f2ca, v115
	v_min_f32_e32 v106, 0x7149f2ca, v106
	v_min_f32_e32 v107, 0x7149f2ca, v107
	v_min_f32_e32 v98, 0x7149f2ca, v98
	v_min_f32_e32 v99, 0x7149f2ca, v99
	v_min_f32_e32 v88, 0x7149f2ca, v88
	v_min_f32_e32 v89, 0x7149f2ca, v89
	v_min_f32_e32 v80, 0x7149f2ca, v80
	v_min_f32_e32 v81, 0x7149f2ca, v81
	v_cvt_pk_bf16_f32 v10, v10, v11
	v_add_f32_e32 v11, 1.0, v13
	v_add_f32_e32 v13, 1.0, v14
	v_cvt_pk_bf16_f32 v129, v122, v123
	v_add_u32_e32 v122, 0x800, v142
	v_cvt_pk_bf16_f32 v121, v114, v115
	v_add_u32_e32 v114, 0x1000, v142
	v_cvt_pk_bf16_f32 v113, v106, v107
	v_add_u32_e32 v106, 0x1800, v142
	v_cvt_pk_bf16_f32 v105, v98, v99
	v_add_u32_e32 v98, 0x2000, v142
	v_cvt_pk_bf16_f32 v95, v88, v89
	v_add_u32_e32 v88, 0x2800, v142
	v_cvt_pk_bf16_f32 v87, v80, v81
	v_add_u32_e32 v80, 0x3000, v142
	v_min_f32_e32 v11, 0x7149f2ca, v11
	v_min_f32_e32 v13, 0x7149f2ca, v13
	global_store_dwordx4 v142, v[126:129], s[54:55] sc0 sc1 nt
	global_store_dwordx4 v122, v[118:121], s[54:55] sc0 sc1 nt
	global_store_dwordx4 v114, v[110:113], s[54:55] sc0 sc1 nt
	global_store_dwordx4 v106, v[102:105], s[54:55] sc0 sc1 nt
; __device__ __forceinline__ float sigm(float v) { return __builtin_amdgcn_rcpf(1.0f + __builtin_amdgcn_exp2f(-LOG2E * v)); }
; __device__ __forceinline__ unsigned cvt_pk_bf16(float lo, float hi) { f32x2_t v = {lo, hi}; bf16x2_t b = __builtin_convertvector(v, bf16x2_t); return __builtin_bit_cast(unsigned, b); }
; template <int MODE> __device__ __forceinline__ float actf(float v) {
;     if (MODE == 1) return v * sigm(v);
;     if (MODE == 2) return fminf(1.0f + __builtin_amdgcn_exp2f(-LOG2E * v), 1e30f);
;     template <int MODE> __device__ __forceinline__ void run(const f32x4 (&acc)[2][2][4][2], const Unit& u, int wr, int wc, int fr, int fq) const {
;     ...
;         for (int bj = 0; bj < 2; ++bj) {
; #pragma unroll
;             for (int ai = 0; ai < 2; ++ai)
; #pragma unroll
;                 for (int m = 0; m < 4; ++m) { const unsigned off = off0 + ((MODE == 2) ? (unsigned)(((ai * 4 + m) * 2 + bj) * 1024) : (unsigned)((ai * HALF + m * 16) * 512 + bj * HALF) * 2u);
;                     const f32x4 v0 = acc[ai][bj][m][0], v1 = acc[ai][bj][m][1];
;                     u32x4 w; w.x = cvt_pk_bf16(actf<MODE>(v0[0]), actf<MODE>(v0[1])); w.y = cvt_pk_bf16(actf<MODE>(v0[2]), actf<MODE>(v0[3]));
;                     w.z = cvt_pk_bf16(actf<MODE>(v1[0]), actf<MODE>(v1[1])); w.w = cvt_pk_bf16(actf<MODE>(v1[2]), actf<MODE>(v1[3]));
;                     *(u32x4*)(base + off) = w; }
	global_store_dwordx4 v98, v[92:95], s[54:55] sc0 sc1 nt
	global_store_dwordx4 v88, v[84:87], s[54:55] sc0 sc1 nt
	global_store_dwordx4 v80, v[76:79], s[54:55] sc0 sc1 nt
	v_add_u32_e32 v12, 0x400, v142
	v_cvt_pk_bf16_f32 v11, v11, v13
	global_store_dwordx4 v12, v[8:11], s[54:55] sc0 sc1 nt
	v_mul_f32_e32 v13, 0xbfb8aa3b, v57
	v_exp_f32_e32 v13, v13
	v_mul_f32_e32 v8, 0xbfb8aa3b, v60
	v_mul_f32_e32 v9, 0xbfb8aa3b, v61
	v_exp_f32_e32 v8, v8
	v_exp_f32_e32 v9, v9
	v_mul_f32_e32 v10, 0xbfb8aa3b, v62
	v_mul_f32_e32 v11, 0xbfb8aa3b, v63
	v_exp_f32_e32 v10, v10
	v_exp_f32_e32 v11, v11
	v_add_f32_e32 v8, 1.0, v8
	v_add_f32_e32 v9, 1.0, v9
	v_min_f32_e32 v8, 0x7149f2ca, v8
	v_min_f32_e32 v9, 0x7149f2ca, v9
	v_cvt_pk_bf16_f32 v8, v8, v9
	v_add_f32_e32 v9, 1.0, v10
	v_add_f32_e32 v10, 1.0, v11
	v_mul_f32_e32 v11, 0xbfb8aa3b, v56
	v_exp_f32_e32 v11, v11
	v_min_f32_e32 v9, 0x7149f2ca, v9
	v_min_f32_e32 v10, 0x7149f2ca, v10
	v_cvt_pk_bf16_f32 v9, v9, v10
	v_add_f32_e32 v10, 1.0, v11
	v_add_f32_e32 v11, 1.0, v13
	v_mul_f32_e32 v13, 0xbfb8aa3b, v58
	v_mul_f32_e32 v14, 0xbfb8aa3b, v59
	v_exp_f32_e32 v13, v13
	v_exp_f32_e32 v14, v14
	v_min_f32_e32 v10, 0x7149f2ca, v10
	v_min_f32_e32 v11, 0x7149f2ca, v11
	v_cvt_pk_bf16_f32 v10, v10, v11
	v_add_f32_e32 v11, 1.0, v13
	v_add_f32_e32 v13, 1.0, v14
	v_min_f32_e32 v11, 0x7149f2ca, v11
	v_min_f32_e32 v13, 0x7149f2ca, v13
	v_add_u32_e32 v12, 0xc00, v142
	v_cvt_pk_bf16_f32 v11, v11, v13
	global_store_dwordx4 v12, v[8:11], s[54:55] sc0 sc1 nt
	v_mul_f32_e32 v13, 0xbfb8aa3b, v49
	v_exp_f32_e32 v13, v13
	v_mul_f32_e32 v8, 0xbfb8aa3b, v52
	v_mul_f32_e32 v9, 0xbfb8aa3b, v53
	v_exp_f32_e32 v8, v8
	v_exp_f32_e32 v9, v9
	v_mul_f32_e32 v10, 0xbfb8aa3b, v54
	v_mul_f32_e32 v11, 0xbfb8aa3b, v55
	v_exp_f32_e32 v10, v10
	v_exp_f32_e32 v11, v11
	v_add_f32_e32 v8, 1.0, v8
	v_add_f32_e32 v9, 1.0, v9
	v_min_f32_e32 v8, 0x7149f2ca, v8
	v_min_f32_e32 v9, 0x7149f2ca, v9
	v_cvt_pk_bf16_f32 v8, v8, v9
	v_add_f32_e32 v9, 1.0, v10
	v_add_f32_e32 v10, 1.0, v11
	v_mul_f32_e32 v11, 0xbfb8aa3b, v48
	v_exp_f32_e32 v11, v11
	v_min_f32_e32 v9, 0x7149f2ca, v9
	v_min_f32_e32 v10, 0x7149f2ca, v10
	v_cvt_pk_bf16_f32 v9, v9, v10
	v_add_f32_e32 v10, 1.0, v11
	v_add_f32_e32 v11, 1.0, v13
	v_mul_f32_e32 v13, 0xbfb8aa3b, v50
	v_mul_f32_e32 v14, 0xbfb8aa3b, v51
	v_exp_f32_e32 v13, v13
	v_exp_f32_e32 v14, v14
	v_min_f32_e32 v10, 0x7149f2ca, v10
	v_min_f32_e32 v11, 0x7149f2ca, v11
	v_cvt_pk_bf16_f32 v10, v10, v11
	v_add_f32_e32 v11, 1.0, v13
	v_add_f32_e32 v13, 1.0, v14
	v_min_f32_e32 v11, 0x7149f2ca, v11
	v_min_f32_e32 v13, 0x7149f2ca, v13
	v_add_u32_e32 v12, 0x1400, v142
	v_cvt_pk_bf16_f32 v11, v11, v13
	global_store_dwordx4 v12, v[8:11], s[54:55] sc0 sc1 nt
	v_mul_f32_e32 v13, 0xbfb8aa3b, v41
	v_exp_f32_e32 v13, v13
	v_mul_f32_e32 v8, 0xbfb8aa3b, v44
	v_mul_f32_e32 v9, 0xbfb8aa3b, v45
	v_exp_f32_e32 v8, v8
	v_exp_f32_e32 v9, v9
	v_mul_f32_e32 v10, 0xbfb8aa3b, v46
	v_mul_f32_e32 v11, 0xbfb8aa3b, v47
	v_exp_f32_e32 v10, v10
	v_exp_f32_e32 v11, v11
	v_add_f32_e32 v8, 1.0, v8
	v_add_f32_e32 v9, 1.0, v9
	v_min_f32_e32 v8, 0x7149f2ca, v8
	v_min_f32_e32 v9, 0x7149f2ca, v9
	v_cvt_pk_bf16_f32 v8, v8, v9
	v_add_f32_e32 v9, 1.0, v10
	v_add_f32_e32 v10, 1.0, v11
	v_mul_f32_e32 v11, 0xbfb8aa3b, v40
	v_exp_f32_e32 v11, v11
	v_min_f32_e32 v9, 0x7149f2ca, v9
	v_min_f32_e32 v10, 0x7149f2ca, v10
	v_cvt_pk_bf16_f32 v9, v9, v10
	v_add_f32_e32 v10, 1.0, v11
	v_add_f32_e32 v11, 1.0, v13
	v_mul_f32_e32 v13, 0xbfb8aa3b, v42
	v_mul_f32_e32 v14, 0xbfb8aa3b, v43
	v_exp_f32_e32 v13, v13
	v_exp_f32_e32 v14, v14
	v_min_f32_e32 v10, 0x7149f2ca, v10
	v_min_f32_e32 v11, 0x7149f2ca, v11
	v_cvt_pk_bf16_f32 v10, v10, v11
	v_add_f32_e32 v11, 1.0, v13
	v_add_f32_e32 v13, 1.0, v14
	v_min_f32_e32 v11, 0x7149f2ca, v11
	v_min_f32_e32 v13, 0x7149f2ca, v13
	v_add_u32_e32 v12, 0x1c00, v142
	v_cvt_pk_bf16_f32 v11, v11, v13
	global_store_dwordx4 v12, v[8:11], s[54:55] sc0 sc1 nt
	v_mul_f32_e32 v13, 0xbfb8aa3b, v33
	v_exp_f32_e32 v13, v13
	v_mul_f32_e32 v8, 0xbfb8aa3b, v36
	v_mul_f32_e32 v9, 0xbfb8aa3b, v37
	v_exp_f32_e32 v8, v8
	v_exp_f32_e32 v9, v9
	v_mul_f32_e32 v10, 0xbfb8aa3b, v38
	v_mul_f32_e32 v11, 0xbfb8aa3b, v39
	v_exp_f32_e32 v10, v10
	v_exp_f32_e32 v11, v11
	v_add_f32_e32 v8, 1.0, v8
	v_add_f32_e32 v9, 1.0, v9
	v_min_f32_e32 v8, 0x7149f2ca, v8
	v_min_f32_e32 v9, 0x7149f2ca, v9
; __device__ __forceinline__ float sigm(float v) { return __builtin_amdgcn_rcpf(1.0f + __builtin_amdgcn_exp2f(-LOG2E * v)); }
; __device__ __forceinline__ unsigned cvt_pk_bf16(float lo, float hi) { f32x2_t v = {lo, hi}; bf16x2_t b = __builtin_convertvector(v, bf16x2_t); return __builtin_bit_cast(unsigned, b); }
; template <int MODE> __device__ __forceinline__ float actf(float v) {
;     if (MODE == 1) return v * sigm(v);
;     if (MODE == 2) return fminf(1.0f + __builtin_amdgcn_exp2f(-LOG2E * v), 1e30f);
;     template <int MODE> __device__ __forceinline__ void run(const f32x4 (&acc)[2][2][4][2], const Unit& u, int wr, int wc, int fr, int fq) const {
;     ...
;         for (int bj = 0; bj < 2; ++bj) {
; #pragma unroll
;             for (int ai = 0; ai < 2; ++ai)
; #pragma unroll
;                 for (int m = 0; m < 4; ++m) { const unsigned off = off0 + ((MODE == 2) ? (unsigned)(((ai * 4 + m) * 2 + bj) * 1024) : (unsigned)((ai * HALF + m * 16) * 512 + bj * HALF) * 2u);
;                     const f32x4 v0 = acc[ai][bj][m][0], v1 = acc[ai][bj][m][1];
;                     u32x4 w; w.x = cvt_pk_bf16(actf<MODE>(v0[0]), actf<MODE>(v0[1])); w.y = cvt_pk_bf16(actf<MODE>(v0[2]), actf<MODE>(v0[3]));
;                     w.z = cvt_pk_bf16(actf<MODE>(v1[0]), actf<MODE>(v1[1])); w.w = cvt_pk_bf16(actf<MODE>(v1[2]), actf<MODE>(v1[3]));
;                     *(u32x4*)(base + off) = w; }
	v_cvt_pk_bf16_f32 v8, v8, v9
	v_add_f32_e32 v9, 1.0, v10
	v_add_f32_e32 v10, 1.0, v11
	v_mul_f32_e32 v11, 0xbfb8aa3b, v32
	v_exp_f32_e32 v11, v11
	v_min_f32_e32 v9, 0x7149f2ca, v9
	v_min_f32_e32 v10, 0x7149f2ca, v10
	v_cvt_pk_bf16_f32 v9, v9, v10
	v_add_f32_e32 v10, 1.0, v11
	v_add_f32_e32 v11, 1.0, v13
	v_mul_f32_e32 v13, 0xbfb8aa3b, v34
	v_mul_f32_e32 v14, 0xbfb8aa3b, v35
	v_exp_f32_e32 v13, v13
	v_exp_f32_e32 v14, v14
	v_min_f32_e32 v10, 0x7149f2ca, v10
	v_min_f32_e32 v11, 0x7149f2ca, v11
	v_cvt_pk_bf16_f32 v10, v10, v11
	v_add_f32_e32 v11, 1.0, v13
	v_add_f32_e32 v13, 1.0, v14
	v_min_f32_e32 v11, 0x7149f2ca, v11
	v_min_f32_e32 v13, 0x7149f2ca, v13
	v_add_u32_e32 v12, 0x2400, v142
	v_cvt_pk_bf16_f32 v11, v11, v13
	global_store_dwordx4 v12, v[8:11], s[54:55] sc0 sc1 nt
	v_mul_f32_e32 v13, 0xbfb8aa3b, v25
	v_exp_f32_e32 v13, v13
	v_mul_f32_e32 v8, 0xbfb8aa3b, v28
	v_mul_f32_e32 v9, 0xbfb8aa3b, v29
	v_exp_f32_e32 v8, v8
	v_exp_f32_e32 v9, v9
	v_mul_f32_e32 v10, 0xbfb8aa3b, v30
	v_mul_f32_e32 v11, 0xbfb8aa3b, v31
	v_exp_f32_e32 v10, v10
	v_exp_f32_e32 v11, v11
	v_add_f32_e32 v8, 1.0, v8
	v_add_f32_e32 v9, 1.0, v9
	v_min_f32_e32 v8, 0x7149f2ca, v8
	v_min_f32_e32 v9, 0x7149f2ca, v9
	v_cvt_pk_bf16_f32 v8, v8, v9
	v_add_f32_e32 v9, 1.0, v10
	v_add_f32_e32 v10, 1.0, v11
	v_mul_f32_e32 v11, 0xbfb8aa3b, v24
	v_exp_f32_e32 v11, v11
	v_min_f32_e32 v9, 0x7149f2ca, v9
	v_min_f32_e32 v10, 0x7149f2ca, v10
	v_cvt_pk_bf16_f32 v9, v9, v10
	v_add_f32_e32 v10, 1.0, v11
	v_add_f32_e32 v11, 1.0, v13
	v_mul_f32_e32 v13, 0xbfb8aa3b, v26
	v_mul_f32_e32 v14, 0xbfb8aa3b, v27
	v_exp_f32_e32 v13, v13
	v_exp_f32_e32 v14, v14
	v_min_f32_e32 v10, 0x7149f2ca, v10
	v_min_f32_e32 v11, 0x7149f2ca, v11
	v_cvt_pk_bf16_f32 v10, v10, v11
	v_add_f32_e32 v11, 1.0, v13
	v_add_f32_e32 v13, 1.0, v14
	v_min_f32_e32 v11, 0x7149f2ca, v11
	v_min_f32_e32 v13, 0x7149f2ca, v13
	v_add_u32_e32 v12, 0x2c00, v142
	v_cvt_pk_bf16_f32 v11, v11, v13
	global_store_dwordx4 v12, v[8:11], s[54:55] sc0 sc1 nt
	v_mul_f32_e32 v13, 0xbfb8aa3b, v17
	v_exp_f32_e32 v13, v13
	v_mul_f32_e32 v8, 0xbfb8aa3b, v20
	v_mul_f32_e32 v9, 0xbfb8aa3b, v21
	v_exp_f32_e32 v8, v8
	v_exp_f32_e32 v9, v9
	v_mul_f32_e32 v10, 0xbfb8aa3b, v22
	v_mul_f32_e32 v11, 0xbfb8aa3b, v23
	v_exp_f32_e32 v10, v10
	v_exp_f32_e32 v11, v11
	v_add_f32_e32 v8, 1.0, v8
	v_add_f32_e32 v9, 1.0, v9
	v_min_f32_e32 v8, 0x7149f2ca, v8
	v_min_f32_e32 v9, 0x7149f2ca, v9
	v_cvt_pk_bf16_f32 v8, v8, v9
	v_add_f32_e32 v9, 1.0, v10
	v_add_f32_e32 v10, 1.0, v11
	v_mul_f32_e32 v11, 0xbfb8aa3b, v16
	v_exp_f32_e32 v11, v11
	v_mul_f32_e32 v4, 0xbfb8aa3b, v4
	v_mul_f32_e32 v5, 0xbfb8aa3b, v5
	v_exp_f32_e32 v4, v4
	v_exp_f32_e32 v5, v5
	v_min_f32_e32 v9, 0x7149f2ca, v9
	v_min_f32_e32 v10, 0x7149f2ca, v10
	v_mul_f32_e32 v6, 0xbfb8aa3b, v6
	v_mul_f32_e32 v7, 0xbfb8aa3b, v7
	v_mul_f32_e32 v0, 0xbfb8aa3b, v0
	v_mul_f32_e32 v1, 0xbfb8aa3b, v1
	v_cvt_pk_bf16_f32 v9, v9, v10
	v_add_f32_e32 v10, 1.0, v11
	v_add_f32_e32 v11, 1.0, v13
	v_mul_f32_e32 v13, 0xbfb8aa3b, v18
	v_mul_f32_e32 v14, 0xbfb8aa3b, v19
	v_exp_f32_e32 v6, v6
	v_exp_f32_e32 v7, v7
	v_exp_f32_e32 v0, v0
	v_exp_f32_e32 v1, v1
	v_exp_f32_e32 v13, v13
	v_exp_f32_e32 v14, v14
	v_mul_f32_e32 v2, 0xbfb8aa3b, v2
	v_mul_f32_e32 v3, 0xbfb8aa3b, v3
	v_add_f32_e32 v4, 1.0, v4
	v_add_f32_e32 v5, 1.0, v5
	v_exp_f32_e32 v2, v2
	v_exp_f32_e32 v3, v3
	v_min_f32_e32 v4, 0x7149f2ca, v4
	v_min_f32_e32 v5, 0x7149f2ca, v5
	v_min_f32_e32 v10, 0x7149f2ca, v10
	v_min_f32_e32 v11, 0x7149f2ca, v11
	v_cvt_pk_bf16_f32 v4, v4, v5
	v_add_f32_e32 v5, 1.0, v6
	v_add_f32_e32 v6, 1.0, v7
	v_add_f32_e32 v0, 1.0, v0
	v_add_f32_e32 v1, 1.0, v1
	v_cvt_pk_bf16_f32 v10, v10, v11
	v_add_f32_e32 v11, 1.0, v13
	v_add_f32_e32 v13, 1.0, v14
	v_min_f32_e32 v5, 0x7149f2ca, v5
	v_min_f32_e32 v6, 0x7149f2ca, v6
	v_min_f32_e32 v0, 0x7149f2ca, v0
	v_min_f32_e32 v1, 0x7149f2ca, v1
	v_min_f32_e32 v11, 0x7149f2ca, v11
	v_min_f32_e32 v13, 0x7149f2ca, v13
	v_cvt_pk_bf16_f32 v5, v5, v6
	v_cvt_pk_bf16_f32 v6, v0, v1
	v_add_f32_e32 v0, 1.0, v2
	v_add_f32_e32 v1, 1.0, v3
	v_add_u32_e32 v12, 0x3400, v142
	v_cvt_pk_bf16_f32 v11, v11, v13
	v_min_f32_e32 v0, 0x7149f2ca, v0
	v_min_f32_e32 v1, 0x7149f2ca, v1
	global_store_dwordx4 v12, v[8:11], s[54:55] sc0 sc1 nt
	v_cvt_pk_bf16_f32 v7, v0, v1
	s_nop 0
	v_add_u32_e32 v8, 0x3c00, v142
	global_store_dwordx4 v8, v[4:7], s[54:55] sc0 sc1 nt
